# four-workgroup counter barrier instead of the grid barrier at the scores->attention-out and ffn-up->ffn-down seams
# speedup vs baseline: 1.0000x; 1.0000x over previous
.LBB0_817:
	s_add_i32 s5, s62, 1
	s_cmp_ge_i32 s5, s63
	s_cbranch_scc1 .LBB0_831
	s_add_i32 s0, s62, -2
	s_cmp_lt_u32 s0, 32
	s_cbranch_scc0 .Lgb_no
	s_and_b32 s0, s0, 7
	s_cmp_eq_u32 s0, 3
	s_cbranch_scc1 .Lgb_do
	s_cmp_eq_u32 s0, 6
	s_cbranch_scc0 .Lgb_no
.Lgb_do:
	s_waitcnt vmcnt(0) lgkmcnt(0)
	s_barrier
	s_getreg_b32 s0, hwreg(HW_REG_HW_ID, 0, 6)
	s_lshl_b32 s0, s0, 2
	s_add_i32 s0, s0, 0x20200
	v_mov_b32_e32 v0, s0
	ds_read_b32 v0, v0
	s_waitcnt lgkmcnt(0)
	v_readfirstlane_b32 s0, v0
	s_cmp_lg_u32 s0, 0
	s_cbranch_scc1 .Lgb_join
	s_mov_b64 s[6:7], exec
	s_mov_b64 exec, 1
	v_mov_b32_e32 v1, 0x201a0
	ds_read_b32 v2, v1
	s_load_dwordx2 s[2:3], s[92:93], 0xa8
	s_waitcnt lgkmcnt(0)
	v_readfirstlane_b32 s1, v2
	s_add_i32 s1, s1, 1
	v_mov_b32_e32 v2, s1
	ds_write_b32 v1, v2
	s_lshl_b32 s1, s1, 2
	s_and_b32 s4, s90, 63
	s_lshl_b32 s4, s4, 4
	s_add_u32 s2, s2, s4
	s_addc_u32 s3, s3, 0
	s_add_u32 s2, s2, 0x2da03600
	s_addc_u32 s3, s3, 0
	buffer_wbl2 sc1
	s_waitcnt vmcnt(0)
	v_mov_b32_e32 v0, 0
	v_mov_b32_e32 v2, 1
	global_atomic_add v0, v2, s[2:3]
	s_waitcnt vmcnt(0)
	s_mov_b32 s0, 0
.Lgb_spin:
	s_sleep 1
	global_load_dword v2, v0, s[2:3] sc1
	s_add_i32 s0, s0, 1
	s_waitcnt vmcnt(0)
	v_readfirstlane_b32 s4, v2
	s_cmp_ge_u32 s4, s1
	s_cbranch_scc1 .Lgb_done
	s_cmp_lt_u32 s0, 0x20000
	s_cbranch_scc1 .Lgb_spin
.Lgb_done:
	buffer_inv sc1
	s_waitcnt vmcnt(0) lgkmcnt(0)
	s_mov_b64 exec, s[6:7]
.Lgb_join:
	s_barrier
	s_branch .LBB0_831
.Lgb_no:
	v_readlane_b32 s0, v255, 31
	v_readlane_b32 s1, v255, 32
	s_and_b64 vcc, exec, s[0:1]
	s_cbranch_vccz .LBB0_830
	s_mov_b32 s0, -1
	s_waitcnt vmcnt(0)
	s_waitcnt vmcnt(0) lgkmcnt(0)
	s_barrier
	s_getreg_b32 s1, hwreg(HW_REG_HW_ID, 0, 6)
	s_and_b32 s1, s1, 63
	s_lshl_b32 s1, s1, 2
	s_add_i32 s1, s1, 0
	s_add_i32 s1, s1, 0x20200
	v_mov_b32_e32 v0, s1
	ds_read_b32 v0, v0
	v_mbcnt_lo_u32_b32 v1, s0, 0
	v_mbcnt_hi_u32_b32 v1, s0, v1
	s_waitcnt lgkmcnt(0)
	v_readfirstlane_b32 s0, v0
	s_lshl_b32 s0, s0, 6
	v_sub_u32_e32 v0, 0, v1
	v_cmp_eq_u32_e32 vcc, s0, v0
	s_and_saveexec_b64 s[0:1], vcc
	s_cbranch_execz .LBB0_869
	v_readlane_b32 s2, v255, 17
	s_waitcnt vmcnt(0) expcnt(0) lgkmcnt(0)
	s_nop 0
	v_mov_b32_e32 v0, s2
	ds_read_b32 v2, v0
	v_readlane_b32 s2, v255, 18
	s_waitcnt lgkmcnt(0)
	v_cmp_ne_u32_e32 vcc, 0, v2
	v_mov_b32_e32 v0, s2
	ds_read_b32 v0, v0
	s_cbranch_vccnz .LBB0_837
	s_mov_b32 s4, 1
	s_branch .LBB0_823
